# peeled first iteration plus leading-half extra barrier behind the epilogue's first loads and removal of a redundant second zeroing run in three LoRA-up GEMMs
# speedup vs baseline: 1.0097x; 1.0024x over previous
;     __device__ __forceinline__ void operator()(const f32x4 (&acc)[2][2][4][2], const Unit& u, int wr, int wc, int fr, int fq) const {
;         EPI_ROWS_PERM
; #pragma unroll
;         for (int ai = 0; ai < 2; ++ai)
; #pragma unroll
;             for (int m = 0; m < 4; ++m) { const size_t off = (size_t)(row0 + ai * 128 + m * 16) * DM + colt;
; #pragma unroll
;                 for (int bj = 0; bj < 2; ++bj) {
;                     const h16x8 x = *(const h16x8*)(X + off + bj * 128);
.Lg4x_61:
	v_lshl_add_u32 v144, s35, 8, v146
	v_lshl_or_b32 v142, s50, 8, v148
	v_ashrrev_i32_e32 v145, 31, v144
	v_ashrrev_i32_e32 v143, 31, v142
	v_lshlrev_b64 v[140:141], 11, v[144:145]
	v_lshl_add_u64 v[140:141], v[140:141], 0, v[142:143]
	v_lshlrev_b64 v[140:141], 1, v[140:141]
	v_lshl_add_u64 v[154:155], s[94:95], 0, v[140:141]
	s_mov_b32 s101, 0
	global_load_dwordx4 v[158:161], v[154:155], off
	global_load_dwordx4 v[162:165], v[154:155], off offset:256
	s_mov_b32 s100, 0x10000
	v_lshl_add_u64 v[232:233], v[154:155], 0, s[100:101]
	global_load_dwordx4 v[166:169], v[232:233], off
	global_load_dwordx4 v[170:173], v[232:233], off offset:256
	s_mov_b32 s100, 0x20000
	v_lshl_add_u64 v[232:233], v[154:155], 0, s[100:101]
	global_load_dwordx4 v[174:177], v[232:233], off
	global_load_dwordx4 v[178:181], v[232:233], off offset:256
	s_mov_b32 s100, 0x30000
	v_lshl_add_u64 v[232:233], v[154:155], 0, s[100:101]
	global_load_dwordx4 v[182:185], v[232:233], off
	global_load_dwordx4 v[186:189], v[232:233], off offset:256
	s_mov_b32 s100, 0x80000
	v_lshl_add_u64 v[232:233], v[154:155], 0, s[100:101]
	global_load_dwordx4 v[190:193], v[232:233], off
	global_load_dwordx4 v[194:197], v[232:233], off offset:256
	s_mov_b32 s100, 0x90000
	v_lshl_add_u64 v[232:233], v[154:155], 0, s[100:101]
	global_load_dwordx4 v[198:201], v[232:233], off
	global_load_dwordx4 v[202:205], v[232:233], off offset:256
	s_mov_b32 s100, 0xa0000
	v_lshl_add_u64 v[232:233], v[154:155], 0, s[100:101]
	global_load_dwordx4 v[212:215], v[232:233], off
	global_load_dwordx4 v[220:223], v[232:233], off offset:256
	s_mov_b32 s100, 0xb0000
	v_lshl_add_u64 v[232:233], v[154:155], 0, s[100:101]
	global_load_dwordx4 v[224:227], v[232:233], off
	global_load_dwordx4 v[228:231], v[232:233], off offset:256
	s_mov_b64 s[4:5], 0xb0000
	s_and_b64 vcc, exec, s[38:39]
	s_mov_b32 s50, s72
	s_mov_b64 s[26:27], s[40:41]
	s_mov_b64 s[22:23], s[0:1]
	s_cmpk_gt_u32 s46, 0xff
	s_cbranch_scc1 .Lgx0
	s_barrier

;     __device__ __forceinline__ void operator()(const f32x4 (&acc)[2][2][4][2], const Unit& u, int wr, int wc, int fr, int fq) const {
;         const int row0 = u.pm * 256 + wr * 64 + fr, f0 = u.pn * 128 + wc * 32 + 8 * fq;
;         f32x4 w0[2], w1[2], w2[2], bb[2];
; #pragma unroll
;         for (int n = 0; n < 2; ++n) { w0[n] = *(const f32x4*)(cw + f0 + 4 * n); w1[n] = *(const f32x4*)(cw + FF + f0 + 4 * n); w2[n] = *(const f32x4*)(cw + 2 * FF + f0 + 4 * n); bb[n] = *(const f32x4*)(cb + f0 + 4 * n); }
.Lg4x_92:
	v_lshl_or_b32 v176, s23, 7, v194
	v_ashrrev_i32_e32 v177, 31, v176
	v_lshlrev_b64 v[66:67], 2, v[176:177]
	v_lshl_add_u64 v[70:71], s[74:75], 0, v[66:67]
	v_lshl_add_u64 v[74:75], s[8:9], 0, v[66:67]
	v_lshl_add_u64 v[78:79], s[70:71], 0, v[66:67]
	v_lshl_add_u64 v[102:103], s[78:79], 0, v[66:67]
	global_load_dwordx4 v[66:69], v[70:71], off offset:16
	global_load_dwordx4 v[90:93], v[70:71], off
	s_nop 0
	global_load_dwordx4 v[70:73], v[74:75], off offset:16
	global_load_dwordx4 v[94:97], v[74:75], off
	s_nop 0
	global_load_dwordx4 v[74:77], v[78:79], off offset:16
	global_load_dwordx4 v[98:101], v[78:79], off
	s_nop 0
	global_load_dwordx4 v[78:81], v[102:103], off offset:16
	s_nop 0
	global_load_dwordx4 v[102:105], v[102:103], off
	s_cmpk_gt_u32 s10, 0xff
	s_cbranch_scc1 .Lgx1
	s_barrier

;     __device__ __forceinline__ void operator()(const f32x4 (&acc)[2][2][4][2], const Unit& u, int wr, int wc, int fr, int fq) const {
;         EPI_ROWS_PERM
; #pragma unroll
;         for (int ai = 0; ai < 2; ++ai)
; #pragma unroll
;             for (int m = 0; m < 4; ++m) { const size_t off = (size_t)(row0 + ai * 128 + m * 16) * DM + colt;
; #pragma unroll
;                 for (int bj = 0; bj < 2; ++bj) {
;                     const h16x8 x = *(const h16x8*)(X + off + bj * 128);
.Lg4x_147:
	v_lshl_add_u32 v144, s22, 8, v146
	v_lshl_or_b32 v142, s35, 8, v148
	v_ashrrev_i32_e32 v145, 31, v144
	v_ashrrev_i32_e32 v143, 31, v142
	v_lshlrev_b64 v[140:141], 11, v[144:145]
	v_lshl_add_u64 v[140:141], v[140:141], 0, v[142:143]
	v_lshlrev_b64 v[140:141], 1, v[140:141]
	v_lshl_add_u64 v[154:155], s[94:95], 0, v[140:141]
	s_mov_b32 s101, 0
	global_load_dwordx4 v[158:161], v[154:155], off
	global_load_dwordx4 v[162:165], v[154:155], off offset:256
	s_mov_b32 s100, 0x10000
	v_lshl_add_u64 v[232:233], v[154:155], 0, s[100:101]
	global_load_dwordx4 v[166:169], v[232:233], off
	global_load_dwordx4 v[170:173], v[232:233], off offset:256
	s_mov_b32 s100, 0x20000
	v_lshl_add_u64 v[232:233], v[154:155], 0, s[100:101]
	global_load_dwordx4 v[174:177], v[232:233], off
	global_load_dwordx4 v[178:181], v[232:233], off offset:256
	s_mov_b32 s100, 0x30000
	v_lshl_add_u64 v[232:233], v[154:155], 0, s[100:101]
	global_load_dwordx4 v[182:185], v[232:233], off
	global_load_dwordx4 v[186:189], v[232:233], off offset:256
	s_mov_b32 s100, 0x80000
	v_lshl_add_u64 v[232:233], v[154:155], 0, s[100:101]
	global_load_dwordx4 v[190:193], v[232:233], off
	global_load_dwordx4 v[194:197], v[232:233], off offset:256
	s_mov_b32 s100, 0x90000
	v_lshl_add_u64 v[232:233], v[154:155], 0, s[100:101]
	global_load_dwordx4 v[198:201], v[232:233], off
	global_load_dwordx4 v[202:205], v[232:233], off offset:256
	s_mov_b32 s100, 0xa0000
	v_lshl_add_u64 v[232:233], v[154:155], 0, s[100:101]
	global_load_dwordx4 v[212:215], v[232:233], off
	global_load_dwordx4 v[220:223], v[232:233], off offset:256
	s_mov_b32 s100, 0xb0000
	v_lshl_add_u64 v[232:233], v[154:155], 0, s[100:101]
	global_load_dwordx4 v[224:227], v[232:233], off
	global_load_dwordx4 v[228:231], v[232:233], off offset:256
	s_mov_b64 s[2:3], 0xb0000
	s_and_b64 vcc, exec, s[38:39]
	s_mov_b32 s22, s40
	s_mov_b64 s[46:47], s[44:45]
	s_mov_b64 s[26:27], s[42:43]
	s_movk_i32 s66, 0x80
	s_cmpk_gt_u32 s62, 0xff
	s_cbranch_scc1 .Lgx2
	s_barrier

; template <class Epi, class AMap>
; __device__ __forceinline__ void gemm_phase(LAS unsigned char* lds, const AMap am, const int lda, const h16* Bt, const int ldb, const int M, const int N, const int K, const Epi& E) {
;     ...
; #pragma unroll
;         for (int a = 0; a < 2; ++a)
; #pragma unroll
;             for (int b = 0; b < 2; ++b)
; #pragma unroll
;                 for (int m = 0; m < 4; ++m)
; #pragma unroll
;                     for (int n = 0; n < 2; ++n) acc[a][b][m][n] = (f32x4){0.f, 0.f, 0.f, 0.f};
;         cur = nxt; cA = nA; cB = nB; ++ui;
.LBB0_619:
	s_ashr_i32 s45, s44, 31
	s_lshl_b64 s[20:21], s[44:45], 17
	s_add_u32 s68, s74, s20
	v_mov_b32_e32 v133, 0
	s_addc_u32 s69, s75, s21
	s_andn2_b64 vcc, exec, s[42:43]
	v_mov_b32_e32 v132, v133
	v_mov_b32_e32 v131, v133
	v_mov_b32_e32 v130, v133
	v_mov_b32_e32 v137, v133
	v_mov_b32_e32 v136, v133
	v_mov_b32_e32 v135, v133
	v_mov_b32_e32 v134, v133
	v_mov_b32_e32 v129, v133
	v_mov_b32_e32 v128, v133
	v_mov_b32_e32 v127, v133
	v_mov_b32_e32 v126, v133
	v_mov_b32_e32 v125, v133
	v_mov_b32_e32 v124, v133
	v_mov_b32_e32 v123, v133
	v_mov_b32_e32 v122, v133
	v_mov_b32_e32 v121, v133
	v_mov_b32_e32 v120, v133
	v_mov_b32_e32 v119, v133
	v_mov_b32_e32 v118, v133
	v_mov_b32_e32 v117, v133
	v_mov_b32_e32 v116, v133
	v_mov_b32_e32 v115, v133
	v_mov_b32_e32 v114, v133
	v_mov_b32_e32 v113, v133
	v_mov_b32_e32 v112, v133
	v_mov_b32_e32 v111, v133
	v_mov_b32_e32 v110, v133
	v_mov_b32_e32 v109, v133
	v_mov_b32_e32 v108, v133
	v_mov_b32_e32 v107, v133
	v_mov_b32_e32 v106, v133
	v_mov_b32_e32 v65, v133
	v_mov_b32_e32 v64, v133
	v_mov_b32_e32 v63, v133
	v_mov_b32_e32 v62, v133
	v_mov_b32_e32 v61, v133
	v_mov_b32_e32 v60, v133
	v_mov_b32_e32 v59, v133
	v_mov_b32_e32 v58, v133
	v_mov_b32_e32 v57, v133
	v_mov_b32_e32 v56, v133
	v_mov_b32_e32 v55, v133
	v_mov_b32_e32 v54, v133
	v_mov_b32_e32 v53, v133
	v_mov_b32_e32 v52, v133
	v_mov_b32_e32 v51, v133
	v_mov_b32_e32 v50, v133
	v_mov_b32_e32 v49, v133
	v_mov_b32_e32 v48, v133
	v_mov_b32_e32 v47, v133
	v_mov_b32_e32 v46, v133
	v_mov_b32_e32 v45, v133
	v_mov_b32_e32 v44, v133
	v_mov_b32_e32 v43, v133
	v_mov_b32_e32 v42, v133
	v_mov_b32_e32 v41, v133
	v_mov_b32_e32 v40, v133
	v_mov_b32_e32 v39, v133
	v_mov_b32_e32 v38, v133
	v_mov_b32_e32 v37, v133
	v_mov_b32_e32 v36, v133
	v_mov_b32_e32 v35, v133
	v_mov_b32_e32 v34, v133
	v_mov_b32_e32 v105, v133
	v_mov_b32_e32 v104, v133
	v_mov_b32_e32 v103, v133
	v_mov_b32_e32 v102, v133
	v_mov_b32_e32 v101, v133
	v_mov_b32_e32 v100, v133
	v_mov_b32_e32 v99, v133
	v_mov_b32_e32 v98, v133
	v_mov_b32_e32 v89, v133
	v_mov_b32_e32 v88, v133
	v_mov_b32_e32 v87, v133
	v_mov_b32_e32 v86, v133
	v_mov_b32_e32 v85, v133
	v_mov_b32_e32 v84, v133
	v_mov_b32_e32 v83, v133
	v_mov_b32_e32 v82, v133
	v_mov_b32_e32 v81, v133
	v_mov_b32_e32 v80, v133
	v_mov_b32_e32 v79, v133
	v_mov_b32_e32 v78, v133
	v_mov_b32_e32 v77, v133
	v_mov_b32_e32 v76, v133
	v_mov_b32_e32 v75, v133
	v_mov_b32_e32 v74, v133
	v_mov_b32_e32 v73, v133
	v_mov_b32_e32 v72, v133
	v_mov_b32_e32 v71, v133
	v_mov_b32_e32 v70, v133
	v_mov_b32_e32 v69, v133
	v_mov_b32_e32 v68, v133
	v_mov_b32_e32 v67, v133
	v_mov_b32_e32 v66, v133
	v_mov_b32_e32 v33, v133
	v_mov_b32_e32 v32, v133
	v_mov_b32_e32 v31, v133
	v_mov_b32_e32 v30, v133
	v_mov_b32_e32 v29, v133
	v_mov_b32_e32 v28, v133
	v_mov_b32_e32 v27, v133
	v_mov_b32_e32 v26, v133
	v_mov_b32_e32 v25, v133
	v_mov_b32_e32 v24, v133
	v_mov_b32_e32 v23, v133
	v_mov_b32_e32 v22, v133
	v_mov_b32_e32 v21, v133
	v_mov_b32_e32 v20, v133
	v_mov_b32_e32 v19, v133
	v_mov_b32_e32 v18, v133
	v_mov_b32_e32 v17, v133
	v_mov_b32_e32 v16, v133
	v_mov_b32_e32 v15, v133
	v_mov_b32_e32 v14, v133
	v_mov_b32_e32 v13, v133
	v_mov_b32_e32 v12, v133
	v_mov_b32_e32 v11, v133
	v_mov_b32_e32 v10, v133
	v_mov_b32_e32 v9, v133
	v_mov_b32_e32 v8, v133
	v_mov_b32_e32 v7, v133
	v_mov_b32_e32 v6, v133
	v_mov_b32_e32 v5, v133
	v_mov_b32_e32 v4, v133
	v_mov_b32_e32 v3, v133
	v_mov_b32_e32 v2, v133
	s_cbranch_vccnz .LBB0_610
	s_and_b64 s[0:1], s[0:1], exec
	s_cselect_b32 s20, s69, s27
	s_cselect_b32 s21, s68, s26
	s_add_u32 s29, s26, 0x100
	s_addc_u32 s45, s27, 0
	s_mov_b32 s26, 0

; template <class Epi, class AMap>
; __device__ __forceinline__ void gemm_phase(LAS unsigned char* lds, const AMap am, const int lda, const h16* Bt, const int ldb, const int M, const int N, const int K, const Epi& E) {
;     ...
; #pragma unroll
;         for (int a = 0; a < 2; ++a)
; #pragma unroll
;             for (int b = 0; b < 2; ++b)
; #pragma unroll
;                 for (int m = 0; m < 4; ++m)
; #pragma unroll
;                     for (int n = 0; n < 2; ++n) acc[a][b][m][n] = (f32x4){0.f, 0.f, 0.f, 0.f};
;         cur = nxt; cA = nA; cB = nB; ++ui;
.LBB0_642:
	s_ashr_i32 s45, s44, 31
	s_lshl_b64 s[20:21], s[44:45], 17
	s_add_u32 s64, s72, s20
	v_mov_b32_e32 v125, 0
	s_addc_u32 s65, s73, s21
	s_andn2_b64 vcc, exec, s[42:43]
	v_mov_b32_e32 v124, v125
	v_mov_b32_e32 v123, v125
	v_mov_b32_e32 v122, v125
	v_mov_b32_e32 v129, v125
	v_mov_b32_e32 v128, v125
	v_mov_b32_e32 v127, v125
	v_mov_b32_e32 v126, v125
	v_mov_b32_e32 v113, v125
	v_mov_b32_e32 v112, v125
	v_mov_b32_e32 v111, v125
	v_mov_b32_e32 v110, v125
	v_mov_b32_e32 v109, v125
	v_mov_b32_e32 v108, v125
	v_mov_b32_e32 v107, v125
	v_mov_b32_e32 v106, v125
	v_mov_b32_e32 v97, v125
	v_mov_b32_e32 v96, v125
	v_mov_b32_e32 v95, v125
	v_mov_b32_e32 v94, v125
	v_mov_b32_e32 v93, v125
	v_mov_b32_e32 v92, v125
	v_mov_b32_e32 v91, v125
	v_mov_b32_e32 v90, v125
	v_mov_b32_e32 v81, v125
	v_mov_b32_e32 v80, v125
	v_mov_b32_e32 v79, v125
	v_mov_b32_e32 v78, v125
	v_mov_b32_e32 v77, v125
	v_mov_b32_e32 v76, v125
	v_mov_b32_e32 v75, v125
	v_mov_b32_e32 v74, v125
	v_mov_b32_e32 v121, v125
	v_mov_b32_e32 v120, v125
	v_mov_b32_e32 v119, v125
	v_mov_b32_e32 v118, v125
	v_mov_b32_e32 v117, v125
	v_mov_b32_e32 v116, v125
	v_mov_b32_e32 v115, v125
	v_mov_b32_e32 v114, v125
	v_mov_b32_e32 v105, v125
	v_mov_b32_e32 v104, v125
	v_mov_b32_e32 v103, v125
	v_mov_b32_e32 v102, v125
	v_mov_b32_e32 v101, v125
	v_mov_b32_e32 v100, v125
	v_mov_b32_e32 v99, v125
	v_mov_b32_e32 v98, v125
	v_mov_b32_e32 v89, v125
	v_mov_b32_e32 v88, v125
	v_mov_b32_e32 v87, v125
	v_mov_b32_e32 v86, v125
	v_mov_b32_e32 v85, v125
	v_mov_b32_e32 v84, v125
	v_mov_b32_e32 v83, v125
	v_mov_b32_e32 v82, v125
	v_mov_b32_e32 v73, v125
	v_mov_b32_e32 v72, v125
	v_mov_b32_e32 v71, v125
	v_mov_b32_e32 v70, v125
	v_mov_b32_e32 v69, v125
	v_mov_b32_e32 v68, v125
	v_mov_b32_e32 v67, v125
	v_mov_b32_e32 v66, v125
	v_mov_b32_e32 v65, v125
	v_mov_b32_e32 v64, v125
	v_mov_b32_e32 v63, v125
	v_mov_b32_e32 v62, v125
	v_mov_b32_e32 v61, v125
	v_mov_b32_e32 v60, v125
	v_mov_b32_e32 v59, v125
	v_mov_b32_e32 v58, v125
	v_mov_b32_e32 v49, v125
	v_mov_b32_e32 v48, v125
	v_mov_b32_e32 v47, v125
	v_mov_b32_e32 v46, v125
	v_mov_b32_e32 v45, v125
	v_mov_b32_e32 v44, v125
	v_mov_b32_e32 v43, v125
	v_mov_b32_e32 v42, v125
	v_mov_b32_e32 v33, v125
	v_mov_b32_e32 v32, v125
	v_mov_b32_e32 v31, v125
	v_mov_b32_e32 v30, v125
	v_mov_b32_e32 v29, v125
	v_mov_b32_e32 v28, v125
	v_mov_b32_e32 v27, v125
	v_mov_b32_e32 v26, v125
	v_mov_b32_e32 v17, v125
	v_mov_b32_e32 v16, v125
	v_mov_b32_e32 v15, v125
	v_mov_b32_e32 v14, v125
	v_mov_b32_e32 v13, v125
	v_mov_b32_e32 v12, v125
	v_mov_b32_e32 v11, v125
	v_mov_b32_e32 v10, v125
	v_mov_b32_e32 v57, v125
	v_mov_b32_e32 v56, v125
	v_mov_b32_e32 v55, v125
	v_mov_b32_e32 v54, v125
	v_mov_b32_e32 v53, v125
	v_mov_b32_e32 v52, v125
	v_mov_b32_e32 v51, v125
	v_mov_b32_e32 v50, v125
	v_mov_b32_e32 v41, v125
	v_mov_b32_e32 v40, v125
	v_mov_b32_e32 v39, v125
	v_mov_b32_e32 v38, v125
	v_mov_b32_e32 v37, v125
	v_mov_b32_e32 v36, v125
	v_mov_b32_e32 v35, v125
	v_mov_b32_e32 v34, v125
	v_mov_b32_e32 v25, v125
	v_mov_b32_e32 v24, v125
	v_mov_b32_e32 v23, v125
	v_mov_b32_e32 v22, v125
	v_mov_b32_e32 v21, v125
	v_mov_b32_e32 v20, v125
	v_mov_b32_e32 v19, v125
	v_mov_b32_e32 v18, v125
	v_mov_b32_e32 v9, v125
	v_mov_b32_e32 v8, v125
	v_mov_b32_e32 v7, v125
	v_mov_b32_e32 v6, v125
	v_mov_b32_e32 v5, v125
	v_mov_b32_e32 v4, v125
	v_mov_b32_e32 v3, v125
	v_mov_b32_e32 v2, v125
	s_cbranch_vccnz .LBB0_633
	s_and_b64 s[0:1], s[0:1], exec
	s_cselect_b32 s20, s65, s27
	s_cselect_b32 s21, s64, s26
	s_add_u32 s29, s26, 0x100
	s_addc_u32 s45, s27, 0
	s_mov_b32 s26, 0

; template <class Epi, class AMap>
; __device__ __forceinline__ void gemm_phase(LAS unsigned char* lds, const AMap am, const int lda, const h16* Bt, const int ldb, const int M, const int N, const int K, const Epi& E) {
;     ...
; #pragma unroll
;         for (int a = 0; a < 2; ++a)
; #pragma unroll
;             for (int b = 0; b < 2; ++b)
; #pragma unroll
;                 for (int m = 0; m < 4; ++m)
; #pragma unroll
;                     for (int n = 0; n < 2; ++n) acc[a][b][m][n] = (f32x4){0.f, 0.f, 0.f, 0.f};
;         cur = nxt; cA = nA; cB = nB; ++ui;
.LBB0_690:
	s_ashr_i32 s45, s44, 31
	s_lshl_b64 s[20:21], s[44:45], 17
	s_add_u32 s64, s72, s20
	v_mov_b32_e32 v137, 0
	s_addc_u32 s65, s73, s21
	s_andn2_b64 vcc, exec, s[42:43]
	v_mov_b32_e32 v136, v137
	v_mov_b32_e32 v135, v137
	v_mov_b32_e32 v134, v137
	v_mov_b32_e32 v133, v137
	v_mov_b32_e32 v132, v137
	v_mov_b32_e32 v131, v137
	v_mov_b32_e32 v130, v137
	v_mov_b32_e32 v129, v137
	v_mov_b32_e32 v128, v137
	v_mov_b32_e32 v127, v137
	v_mov_b32_e32 v126, v137
	v_mov_b32_e32 v125, v137
	v_mov_b32_e32 v124, v137
	v_mov_b32_e32 v123, v137
	v_mov_b32_e32 v122, v137
	v_mov_b32_e32 v121, v137
	v_mov_b32_e32 v120, v137
	v_mov_b32_e32 v119, v137
	v_mov_b32_e32 v118, v137
	v_mov_b32_e32 v117, v137
	v_mov_b32_e32 v116, v137
	v_mov_b32_e32 v115, v137
	v_mov_b32_e32 v114, v137
	v_mov_b32_e32 v113, v137
	v_mov_b32_e32 v112, v137
	v_mov_b32_e32 v111, v137
	v_mov_b32_e32 v110, v137
	v_mov_b32_e32 v109, v137
	v_mov_b32_e32 v108, v137
	v_mov_b32_e32 v107, v137
	v_mov_b32_e32 v106, v137
	v_mov_b32_e32 v65, v137
	v_mov_b32_e32 v64, v137
	v_mov_b32_e32 v63, v137
	v_mov_b32_e32 v62, v137
	v_mov_b32_e32 v61, v137
	v_mov_b32_e32 v60, v137
	v_mov_b32_e32 v59, v137
	v_mov_b32_e32 v58, v137
	v_mov_b32_e32 v57, v137
	v_mov_b32_e32 v56, v137
	v_mov_b32_e32 v55, v137
	v_mov_b32_e32 v54, v137
	v_mov_b32_e32 v53, v137
	v_mov_b32_e32 v52, v137
	v_mov_b32_e32 v51, v137
	v_mov_b32_e32 v50, v137
	v_mov_b32_e32 v49, v137
	v_mov_b32_e32 v48, v137
	v_mov_b32_e32 v47, v137
	v_mov_b32_e32 v46, v137
	v_mov_b32_e32 v45, v137
	v_mov_b32_e32 v44, v137
	v_mov_b32_e32 v43, v137
	v_mov_b32_e32 v42, v137
	v_mov_b32_e32 v41, v137
	v_mov_b32_e32 v40, v137
	v_mov_b32_e32 v39, v137
	v_mov_b32_e32 v38, v137
	v_mov_b32_e32 v37, v137
	v_mov_b32_e32 v36, v137
	v_mov_b32_e32 v35, v137
	v_mov_b32_e32 v34, v137
	v_mov_b32_e32 v105, v137
	v_mov_b32_e32 v104, v137
	v_mov_b32_e32 v103, v137
	v_mov_b32_e32 v102, v137
	v_mov_b32_e32 v101, v137
	v_mov_b32_e32 v100, v137
	v_mov_b32_e32 v99, v137
	v_mov_b32_e32 v98, v137
	v_mov_b32_e32 v97, v137
	v_mov_b32_e32 v96, v137
	v_mov_b32_e32 v95, v137
	v_mov_b32_e32 v94, v137
	v_mov_b32_e32 v93, v137
	v_mov_b32_e32 v92, v137
	v_mov_b32_e32 v91, v137
	v_mov_b32_e32 v90, v137
	v_mov_b32_e32 v81, v137
	v_mov_b32_e32 v80, v137
	v_mov_b32_e32 v79, v137
	v_mov_b32_e32 v78, v137
	v_mov_b32_e32 v77, v137
	v_mov_b32_e32 v76, v137
	v_mov_b32_e32 v75, v137
	v_mov_b32_e32 v74, v137
	v_mov_b32_e32 v73, v137
	v_mov_b32_e32 v72, v137
	v_mov_b32_e32 v71, v137
	v_mov_b32_e32 v70, v137
	v_mov_b32_e32 v69, v137
	v_mov_b32_e32 v68, v137
	v_mov_b32_e32 v67, v137
	v_mov_b32_e32 v66, v137
	v_mov_b32_e32 v33, v137
	v_mov_b32_e32 v32, v137
	v_mov_b32_e32 v31, v137
	v_mov_b32_e32 v30, v137
	v_mov_b32_e32 v29, v137
	v_mov_b32_e32 v28, v137
	v_mov_b32_e32 v27, v137
	v_mov_b32_e32 v26, v137
	v_mov_b32_e32 v25, v137
	v_mov_b32_e32 v24, v137
	v_mov_b32_e32 v23, v137
	v_mov_b32_e32 v22, v137
	v_mov_b32_e32 v21, v137
	v_mov_b32_e32 v20, v137
	v_mov_b32_e32 v19, v137
	v_mov_b32_e32 v18, v137
	v_mov_b32_e32 v17, v137
	v_mov_b32_e32 v16, v137
	v_mov_b32_e32 v15, v137
	v_mov_b32_e32 v14, v137
	v_mov_b32_e32 v13, v137
	v_mov_b32_e32 v12, v137
	v_mov_b32_e32 v11, v137
	v_mov_b32_e32 v10, v137
	v_mov_b32_e32 v9, v137
	v_mov_b32_e32 v8, v137
	v_mov_b32_e32 v7, v137
	v_mov_b32_e32 v6, v137
	v_mov_b32_e32 v5, v137
	v_mov_b32_e32 v4, v137
	v_mov_b32_e32 v3, v137
	v_mov_b32_e32 v2, v137
	s_cbranch_vccnz .LBB0_681
	s_and_b64 s[0:1], s[0:1], exec
	s_cselect_b32 s20, s65, s27
	s_cselect_b32 s21, s64, s26
	s_add_u32 s29, s26, 0x100
	s_addc_u32 s45, s27, 0
	s_mov_b32 s26, 0
